# attention K tiles: 4-bit XOR swizzle (chunk ^ row&15) so ds_read_b128 of K is bank-conflict-free; on top of address diets + static prio
# speedup vs baseline: 1.0029x; 1.0029x over previous
.LBB0_178:
	s_or_b64 exec, exec, s[6:7]
	s_waitcnt lgkmcnt(0)
	s_barrier
	v_mbcnt_lo_u32_b32 v2, -1, 0
	v_mbcnt_hi_u32_b32 v2, -1, v2
	s_load_dwordx2 s[6:7], s[0:1], 0x98
	s_waitcnt lgkmcnt(0)
	s_load_dwordx2 s[8:9], s[0:1], 16
	s_waitcnt lgkmcnt(0)
	s_load_dwordx2 s[10:11], s[0:1], 24
	s_waitcnt lgkmcnt(0)
	s_load_dwordx2 s[12:13], s[0:1], 32
	s_waitcnt lgkmcnt(0)
	s_load_dwordx2 s[14:15], s[0:1], 40
	s_waitcnt lgkmcnt(0)
	s_nop 0
	v_ashrrev_i32_e32 v3, 31, v2
	v_lshlrev_b64 v[4:5], 2, v[2:3]
	v_lshl_add_u64 v[6:7], s[8:9], 0, v[4:5]
	v_lshl_add_u64 v[8:9], s[10:11], 0, v[4:5]
	global_load_dword v10, v[6:7], off
	global_load_dword v11, v[6:7], off offset:256
	global_load_dword v12, v[8:9], off
	global_load_dword v13, v[8:9], off offset:256
	v_lshl_add_u64 v[6:7], s[12:13], 0, v[4:5]
	v_lshl_add_u64 v[4:5], s[14:15], 0, v[4:5]
	global_load_dword v8, v[6:7], off
	global_load_dword v9, v[6:7], off offset:256
	global_load_dword v14, v[4:5], off
	global_load_dword v15, v[4:5], off offset:256
	s_abs_i32 s13, s24
	v_cvt_f32_u32_e32 v3, s13
	v_lshlrev_b32_e32 v2, 2, v2
	v_xor_b32_e32 v6, 4, v2
	v_xor_b32_e32 v7, 8, v2
	v_xor_b32_e32 v16, 16, v2
	v_xor_b32_e32 v17, 32, v2
	v_xor_b32_e32 v18, 64, v2
	v_xor_b32_e32 v19, 0x80, v2
	v_rcp_iflag_f32_e32 v20, v3
	v_readfirstlane_b32 s10, v0
	s_lshr_b32 s10, s10, 4
	s_and_b32 s10, s10, 0xffffffc
	s_add_i32 s10, s10, 0
	s_mov_b32 s8, 0x3fb8aa3b
	s_add_i32 s29, s10, 0x20c00
	s_sub_i32 s15, 0, s13
	s_sub_i32 s11, s24, s17
	s_add_i32 s14, s11, 0x1ff
	s_sub_i32 s11, 0xfffffe01, s11
	s_xor_b32 s28, s14, s24
	s_max_i32 s14, s14, s11
	s_mov_b32 s9, 0xc2ce8ed0
	s_mov_b32 s12, 0x42b17218
	v_mov_b32_e32 v1, 0x7f800000
	s_ashr_i32 s28, s28, 31
	s_load_dwordx2 s[10:11], s[0:1], 48
	s_waitcnt lgkmcnt(0)
	s_mov_b32 s25, 0
	s_waitcnt vmcnt(4)
	v_pk_mul_f32 v[2:3], v[10:11], v[12:13]
	s_nop 0
	v_add_f32_e32 v2, v2, v3
	s_waitcnt vmcnt(0)
	v_pk_mul_f32 v[4:5], v[8:9], v[14:15]
	s_nop 0
	v_add_f32_e32 v3, v4, v5
	ds_bpermute_b32 v4, v6, v2
	ds_bpermute_b32 v5, v6, v3
	v_mul_f32_e32 v8, 0x4f7ffffe, v20
	v_cvt_u32_f32_e32 v8, v8
	v_mov_b32_e32 v6, s29
	s_waitcnt lgkmcnt(1)
	v_add_f32_e32 v2, v2, v4
	s_waitcnt lgkmcnt(0)
	v_add_f32_e32 v3, v3, v5
	ds_bpermute_b32 v4, v7, v2
	ds_bpermute_b32 v5, v7, v3
	v_readfirstlane_b32 s29, v8
	s_mul_i32 s15, s15, s29
	s_mul_hi_u32 s15, s29, s15
	s_waitcnt lgkmcnt(1)
	v_add_f32_e32 v2, v2, v4
	s_waitcnt lgkmcnt(0)
	v_add_f32_e32 v3, v3, v5
	ds_bpermute_b32 v4, v16, v2
	ds_bpermute_b32 v5, v16, v3
	s_add_i32 s29, s29, s15
	s_mul_hi_u32 s15, s14, s29
	s_mul_i32 s29, s15, s13
	s_waitcnt lgkmcnt(1)
	v_add_f32_e32 v2, v2, v4
	s_waitcnt lgkmcnt(0)
	v_add_f32_e32 v3, v3, v5
	ds_bpermute_b32 v4, v17, v2
	ds_bpermute_b32 v5, v17, v3
	s_sub_i32 s14, s14, s29
	s_add_i32 s30, s15, 1
	s_sub_i32 s29, s14, s13
	s_waitcnt lgkmcnt(1)
	v_add_f32_e32 v2, v2, v4
	s_waitcnt lgkmcnt(0)
	v_add_f32_e32 v3, v3, v5
	ds_bpermute_b32 v4, v18, v2
	ds_bpermute_b32 v5, v18, v3
	s_cmp_ge_u32 s14, s13
	s_cselect_b32 s15, s30, s15
	s_cselect_b32 s14, s29, s14
	s_waitcnt lgkmcnt(1)
	v_add_f32_e32 v2, v2, v4
	s_waitcnt lgkmcnt(0)
	v_add_f32_e32 v3, v3, v5
	ds_bpermute_b32 v4, v19, v2
	ds_bpermute_b32 v5, v19, v3
	s_add_i32 s29, s15, 1
	s_cmp_ge_u32 s14, s13
	s_cselect_b32 s13, s29, s15
	s_waitcnt lgkmcnt(1)
	v_add_f32_e32 v2, v2, v4
	s_waitcnt lgkmcnt(0)
	v_add_f32_e32 v3, v3, v5
	v_mul_f32_e32 v4, 0x3fb8aa3b, v2
	v_mul_f32_e32 v5, 0x3fb8aa3b, v3
	v_fma_f32 v7, v2, s8, -v4
	v_rndne_f32_e32 v8, v4
	v_fma_f32 v9, v3, s8, -v5
	v_rndne_f32_e32 v10, v5
	v_fmac_f32_e32 v7, 0x32a5705f, v2
	v_sub_f32_e32 v4, v4, v8
	v_fmac_f32_e32 v9, 0x32a5705f, v3
	v_sub_f32_e32 v5, v5, v10
	v_add_f32_e32 v4, v4, v7
	v_cvt_i32_f32_e32 v8, v8
	v_add_f32_e32 v5, v5, v9
	v_exp_f32_e32 v4, v4
	v_cvt_i32_f32_e32 v10, v10
	v_exp_f32_e32 v5, v5
	v_cmp_ngt_f32_e32 vcc, s9, v2
	v_ldexp_f32 v4, v4, v8
	s_xor_b32 s8, s13, s28
	v_ldexp_f32 v5, v5, v10
	v_cndmask_b32_e32 v4, 0, v4, vcc
	v_cmp_ngt_f32_e32 vcc, s9, v3
	s_sub_i32 s8, s8, s28
	s_cmp_lt_i32 s8, 1
	v_cndmask_b32_e32 v5, 0, v5, vcc
	v_cmp_nlt_f32_e32 vcc, s12, v2
	s_nop 1
	v_cndmask_b32_e32 v2, v1, v4, vcc
	v_cmp_nlt_f32_e32 vcc, s12, v3
	s_nop 1
	v_cndmask_b32_e32 v1, v1, v5, vcc
	v_sub_f32_e32 v1, v2, v1
	v_add_f32_e32 v1, 0x3e4ccccd, v1
	ds_write_b32 v6, v1
	s_waitcnt lgkmcnt(0)
	s_cbranch_scc1 .LBB0_463
	s_add_u32 s38, s6, 0x16100000
	s_addc_u32 s39, s7, 0
	s_add_u32 s40, s6, 0x3e100000
	s_addc_u32 s41, s7, 0
	s_lshl_b32 s8, s8, 1
	s_max_i32 s42, s8, 1
	s_add_u32 s43, s6, 0x16601100
	s_mov_b32 s14, 0xffd7ff00
	s_mov_b32 s28, 0xffd80000
	s_movk_i32 s30, 0xff00
	s_addc_u32 s44, s7, 0
	s_movk_i32 s45, 0x5000
	s_mov_b64 s[12:13], 0x100
	v_mov_b32_e32 v223, 0
	s_brev_b32 s46, -2
	s_add_i32 s47, 0, 0x18000
	s_mov_b32 s15, -1
	s_mov_b32 s29, -1
	s_movk_i32 s48, 0xf0
	s_brev_b32 s49, 1
	s_mov_b32 s50, 0x41000000
	s_movk_i32 s51, 0x100
	s_mov_b32 s31, -1
	s_movk_i32 s52, 0xc000
	v_mov_b32_e32 v1, 0x3727c5ac
	s_mov_b32 s53, 0xf800000
	v_mov_b32_e32 v224, 0x260
	v_mov_b32_e32 v225, 0xff800000
	v_mbcnt_lo_u32_b32 v255, -1, 0
	v_mbcnt_hi_u32_b32 v255, -1, v255
	v_lshrrev_b32_e32 v251, 4, v255
	v_and_b32_e32 v252, 15, v255
	s_and_b32 s98, s19, 1
	s_lshl_b32 s98, s98, 3
	v_or_b32_e32 v253, s98, v251
	v_xor_b32_e32 v252, v252, v253
	v_lshlrev_b32_e32 v252, 4, v252
	v_mul_u32_u24_e32 v251, 0xa000, v251
	v_add_u32_e32 v251, v251, v252
	s_mul_i32 s98, s19, 0x50000
	v_add_u32_e32 v251, s98, v251
	v_xor_b32_e32 v252, 64, v251
	v_add_u32_e32 v252, 0x28000, v252
	v_bfe_u32 v253, v255, 2, 3
	s_and_b32 s98, s19, 1
	s_lshl_b32 s98, s98, 4
	v_or_b32_e32 v253, s98, v253
	v_mul_u32_u24_e32 v253, 0xa000, v253
	v_lshrrev_b32_e32 v254, 5, v255
	v_lshlrev_b32_e32 v254, 6, v254
	v_add_u32_e32 v253, v253, v254
	v_bfe_u32 v254, v255, 4, 1
	v_xor_b32_e32 v254, v254, v255
	v_and_b32_e32 v254, 3, v254
	v_lshlrev_b32_e32 v254, 4, v254
	v_add_u32_e32 v253, v253, v254
	v_xor_b32_e32 v254, 32, v253
	v_add_u32_e32 v254, 0x50000, v254
	v_lshrrev_b32_e32 v2, 3, v255
	v_ashrrev_i32_e32 v3, 5, v255
	v_and_or_b32 v2, v2, 2, v3
	v_lshlrev_b32_e32 v3, 1, v3
	v_bfe_u32 v5, v255, 1, 1
	v_and_b32_e32 v3, 2, v3
	v_and_b32_e32 v6, 12, v255
	v_or3_b32 v5, v6, v3, v5
	v_lshlrev_b32_e32 v2, 11, v2
	v_lshlrev_b32_e32 v7, 3, v255
	v_and_b32_e32 v7, 8, v7
	v_lshlrev_b32_e32 v5, 4, v5
	v_add3_u32 v255, v7, v2, v5
	s_cmp_lt_u32 s19, 4
	s_cbranch_scc1 .Lattn_prio_skip
	s_setprio 1

.LBB0_182:
	s_lshr_b32 s6, s25, 1
	s_mul_i32 s6, s24, s6
	s_add_i32 s34, s17, s6
	s_lshl_b32 s6, s34, 4
	s_and_b32 s36, s6, 0xe00
	s_and_b32 s6, s34, 31
	s_ashr_i32 s8, s34, 8
	s_and_b32 s7, s25, 1
	s_xor_b32 s9, s6, 63
	v_mov_b32_e32 v4, v0
	s_cmp_eq_u32 s7, 0
	s_cselect_b32 s80, s6, s9
	v_readfirstlane_b32 s54, v4
	s_ashr_i32 s87, s54, 6
	s_ashr_i32 s9, s8, 31
	s_ashr_i32 s56, s54, 8
	s_and_b32 s57, s87, 3
	s_lshl_b32 s58, s80, 7
	s_lshl_b64 s[6:7], s[8:9], 13
	s_mul_i32 s88, s8, 0x14000000
	s_mul_hi_i32 s37, s8, 0x14000000
	s_add_u32 s8, s38, s88
	s_addc_u32 s9, s39, s37
	s_lshl_b32 s34, s34, 3
	s_and_b32 s55, s34, 0x700
	s_lshl_b32 s60, s55, 1
	s_add_u32 s8, s8, s60
	s_addc_u32 s9, s9, 0
	s_add_u32 s34, s8, 0x1000
	s_addc_u32 s35, s9, 0
	s_add_u32 s82, s8, 0x2000
	s_addc_u32 s83, s9, 0
	s_lshl_b32 s8, s57, 5
	s_or_b32 s59, s58, s8
	s_or_b32 s6, s59, s6
	s_mul_hi_u32 s9, s6, 0xa000
	s_mul_i32 s58, s7, 0xa000
	s_mul_i32 s8, s6, 0xa000
	s_add_i32 s9, s9, s58
	s_add_u32 s8, s38, s8
	s_addc_u32 s9, s39, s9
	s_add_u32 s58, s8, s60
	s_addc_u32 s60, s9, 0
	s_lshl_b32 s8, s56, 7
	s_ashr_i32 s9, s8, 31
	v_and_b32_e32 v14, 63, v4
	s_lshl_b64 s[8:9], s[8:9], 1
	s_add_u32 s8, s58, s8
	v_mov_b32_e32 v15, v14
	s_addc_u32 s9, s60, s9
	s_lshl_b32 s68, s87, 3
	v_ashrrev_i32_e32 v6, 4, v15
	v_and_b32_e32 v7, 15, v15
	v_add_u32_e32 v2, s68, v6
	s_and_b32 s58, s54, 0x3fffffc0
	s_waitcnt lgkmcnt(0)
	v_bitop3_b32 v3, v2, v7, 15 bitop3:0x6c
	v_mul_lo_u32 v2, v2, s45
	s_lshl_b32 s58, s58, 2
	v_lshl_or_b32 v2, v3, 3, v2
	s_lshl_b32 s61, s87, 11
	s_add_i32 s60, s58, 0
	s_lshl_b32 s58, s87, 1
	s_add_i32 s62, s61, 0
	v_ashrrev_i32_e32 v3, 31, v2
	v_lshl_add_u64 v[2:3], v[2:3], 1, s[34:35]
	s_mov_b32 m0, s62
	s_add_i32 s63, s62, 0x4000
	s_or_b32 s58, s58, 1
	global_load_lds_dwordx4 v[2:3], off
	v_lshl_add_u64 v[2:3], v[2:3], 0, s[12:13]
	s_mov_b32 m0, s63
	s_lshl_b32 s64, s58, 2
	global_load_lds_dwordx4 v[2:3], off
	v_add_u32_e32 v2, s64, v6
	v_bitop3_b32 v3, v2, v7, 15 bitop3:0x6c
	v_mul_lo_u32 v2, v2, s45
	v_lshl_or_b32 v2, v3, 3, v2
	s_lshl_b32 s65, s58, 10
	s_add_i32 s66, s65, 0
	v_ashrrev_i32_e32 v3, 31, v2
	s_andn2_b32 s68, s68, 31
	s_add_i32 s60, s60, 0x20400
	v_lshl_add_u64 v[2:3], v[2:3], 1, s[34:35]
	s_add_i32 s67, s66, 0x4000
	s_lshl_b32 s58, s87, 2
	s_mul_i32 s35, s68, 0xa000
	s_mul_hi_i32 s34, s68, 0xa000
	s_add_u32 s35, s82, s35
	s_mov_b32 m0, s66
	s_addc_u32 s69, s83, s34
	s_and_b32 s34, s54, 0x80
	global_load_lds_dwordx4 v[2:3], off
	v_lshl_add_u64 v[2:3], v[2:3], 0, s[12:13]
	s_mov_b32 m0, s67
	s_lshl_b32 s84, s34, 1
	global_load_lds_dwordx4 v[2:3], off
	v_lshrrev_b32_e32 v2, 2, v15
	s_add_u32 s34, s35, s84
	s_addc_u32 s35, s69, 0
	s_lshl_b32 s69, s87, 4
	v_bfe_u32 v2, v2, 2, 1
	v_bfe_u32 v16, v15, 2, 3
	s_and_b32 s69, s69, 16
	v_xor_b32_e32 v2, v2, v15
	v_or_b32_e32 v6, s69, v16
	v_and_b32_e32 v17, 0xffffffe0, v15
	v_lshlrev_b32_e32 v2, 3, v2
	v_and_b32_e32 v12, 24, v2
	v_mad_u32_u24 v2, v6, s45, v17
	s_lshl_b32 s70, s87, 12
	v_or_b32_e32 v2, v12, v2
	s_add_i32 s72, s70, 0
	v_ashrrev_i32_e32 v3, 31, v2
	s_add_i32 s71, s72, 0x8000
	v_and_b32_e32 v5, 31, v4
	v_lshl_add_u64 v[2:3], v[2:3], 1, s[34:35]
	s_mov_b32 m0, s71
	v_add_u32_e32 v18, 64, v17
	global_load_lds_dwordx4 v[2:3], off
	v_mul_u32_u24_e32 v2, 0x5000, v5
	v_mad_u32_u24 v13, v6, s45, v18
	v_lshlrev_b32_e32 v222, 1, v2
	v_lshl_add_u64 v[2:3], s[8:9], 0, v[222:223]
	v_lshrrev_b32_e32 v4, 1, v4
	v_or_b32_e32 v12, v12, v13
	s_or_b32 s8, s58, 2
	v_and_b32_e32 v222, 16, v4
	v_ashrrev_i32_e32 v13, 31, v12
	s_add_i32 s72, s72, 0x8400
	s_lshl_b32 s9, s8, 2
	v_lshl_add_u64 v[10:11], v[2:3], 0, v[222:223]
	v_lshl_add_u64 v[12:13], v[12:13], 1, s[34:35]
	s_mov_b32 m0, s72
	s_and_b32 s73, s9, 24
	global_load_dwordx4 v[2:5], v[10:11], off offset:192
	global_load_dwordx4 v[6:9], v[10:11], off offset:224
	s_lshl_b32 s74, s8, 10
	global_load_lds_dwordx4 v[12:13], off
	v_or_b32_e32 v12, s73, v16
	v_lshrrev_b32_e32 v13, 2, v12
	v_xor_b32_e32 v13, v13, v15
	v_lshlrev_b32_e32 v13, 3, v13
	v_mad_u32_u24 v12, v12, s45, v17
	v_and_or_b32 v12, v13, 24, v12
	s_add_i32 s75, s74, 0
	s_or_b32 s8, s58, 3
	v_ashrrev_i32_e32 v13, 31, v12
	s_add_i32 s75, s75, 0x8000
	s_lshl_b32 s9, s8, 2
	v_lshl_add_u64 v[12:13], v[12:13], 1, s[34:35]
	s_mov_b32 m0, s75
	s_and_b32 s76, s9, 24
	global_load_lds_dwordx4 v[12:13], off
	v_or_b32_e32 v12, s76, v16
	v_lshrrev_b32_e32 v13, 2, v12
	v_xor_b32_e32 v13, v13, v15
	v_lshlrev_b32_e32 v13, 3, v13
	v_mad_u32_u24 v12, v12, s45, v18
	s_lshl_b32 s77, s8, 10
	v_and_or_b32 v12, v13, 24, v12
	s_add_i32 s78, s77, 0
	v_ashrrev_i32_e32 v13, 31, v12
	s_add_i32 s78, s78, 0x8000
	v_lshl_add_u64 v[12:13], v[12:13], 1, s[34:35]
	s_mov_b32 m0, s78
	s_lshl_b32 s80, s80, 1
	global_load_lds_dwordx4 v[12:13], off
	global_load_dwordx4 v[34:37], v[10:11], off
	global_load_dwordx4 v[38:41], v[10:11], off offset:32
	global_load_dwordx4 v[42:45], v[10:11], off offset:64
	global_load_dwordx4 v[46:49], v[10:11], off offset:96
	global_load_dwordx4 v[50:53], v[10:11], off offset:128
	global_load_dwordx4 v[54:57], v[10:11], off offset:160
	s_add_i32 s81, s62, 0x22400
	s_add_u32 s82, s82, s84
	s_addc_u32 s83, s83, 0
	s_lshl_b32 s8, s56, 14
	s_add_i32 s84, s8, 0
	s_add_i32 s85, s84, 0x10000
	s_add_i32 s86, s59, 0x7fffffff
	s_or_b32 s8, s88, s36
	s_mul_i32 s87, s87, 0x28000
	s_add_u32 s8, s43, s8
	s_mov_b32 s79, 0
	v_lshl_add_u32 v10, v14, 4, s81
	s_addc_u32 s9, s44, s37
	s_add_i32 s88, s87, 0x14000
	v_mov_b32_e32 v186, 0xf149f2ca
	s_mov_b32 s89, 0
	v_mov_b32_e32 v187, 0
	s_waitcnt vmcnt(0)
	ds_write_b128 v10, v[2:5]
	ds_write_b128 v10, v[6:9] offset:1024
	v_mov_b32 v58, 0
	v_mov_b32 v59, 0
	v_mov_b32 v60, 0
	v_mov_b32 v61, 0
	v_mov_b32 v62, 0
	v_mov_b32 v63, 0
	v_mov_b32 v64, 0
	v_mov_b32 v65, 0
	v_mov_b32 v66, 0
	v_mov_b32 v67, 0
	v_mov_b32 v68, 0
	v_mov_b32 v69, 0
	v_mov_b32 v70, 0
	v_mov_b32 v71, 0
	v_mov_b32 v72, 0
	v_mov_b32 v73, 0
	v_mov_b32 v74, 0
	v_mov_b32 v75, 0
	v_mov_b32 v76, 0
	v_mov_b32 v77, 0
	v_mov_b32 v82, 0
	v_mov_b32 v83, 0
	v_mov_b32 v84, 0
	v_mov_b32 v85, 0
	v_mov_b32 v90, 0
	v_mov_b32 v91, 0
	v_mov_b32 v92, 0
	v_mov_b32 v93, 0
	v_mov_b32 v98, 0
	v_mov_b32 v99, 0
	v_mov_b32 v100, 0
	v_mov_b32 v101, 0
	v_mov_b32 v110, 0
	v_mov_b32 v111, 0
	v_mov_b32 v112, 0
	v_mov_b32 v113, 0
	v_mov_b32 v122, 0
	v_mov_b32 v123, 0
	v_mov_b32 v124, 0
	v_mov_b32 v125, 0
	v_mov_b32 v134, 0
	v_mov_b32 v135, 0
	v_mov_b32 v136, 0
	v_mov_b32 v137, 0
	v_mov_b32 v146, 0
	v_mov_b32 v147, 0
	v_mov_b32 v148, 0
	v_mov_b32 v149, 0
	v_mov_b32 v158, 0
	v_mov_b32 v159, 0
	v_mov_b32 v160, 0
	v_mov_b32 v161, 0
	v_mov_b32 v174, 0
	v_mov_b32 v175, 0
	v_mov_b32 v176, 0
	v_mov_b32 v177, 0
	v_mov_b32 v182, 0
	v_mov_b32 v183, 0
	v_mov_b32 v184, 0
	v_mov_b32 v185, 0
	v_mov_b32 v170, 0
	v_mov_b32 v171, 0
	v_mov_b32 v172, 0
	v_mov_b32 v173, 0
	v_mov_b32 v178, 0
	v_mov_b32 v179, 0
	v_mov_b32 v180, 0
	v_mov_b32 v181, 0
	v_mov_b32 v166, 0
	v_mov_b32 v167, 0
	v_mov_b32 v168, 0
	v_mov_b32 v169, 0
	v_mov_b32 v162, 0
	v_mov_b32 v163, 0
	v_mov_b32 v164, 0
	v_mov_b32 v165, 0
	v_mov_b32 v154, 0
	v_mov_b32 v155, 0
	v_mov_b32 v156, 0
	v_mov_b32 v157, 0
	v_mov_b32 v150, 0
	v_mov_b32 v151, 0
	v_mov_b32 v152, 0
	v_mov_b32 v153, 0
	v_mov_b32 v142, 0
	v_mov_b32 v143, 0
	v_mov_b32 v144, 0
	v_mov_b32 v145, 0
	v_mov_b32 v138, 0
	v_mov_b32 v139, 0
	v_mov_b32 v140, 0
	v_mov_b32 v141, 0
	v_mov_b32 v130, 0
	v_mov_b32 v131, 0
	v_mov_b32 v132, 0
	v_mov_b32 v133, 0
	v_mov_b32 v126, 0
	v_mov_b32 v127, 0
	v_mov_b32 v128, 0
	v_mov_b32 v129, 0
	v_mov_b32 v118, 0
	v_mov_b32 v119, 0
	v_mov_b32 v120, 0
	v_mov_b32 v121, 0
	v_mov_b32 v114, 0
	v_mov_b32 v115, 0
	v_mov_b32 v116, 0
	v_mov_b32 v117, 0
	v_mov_b32 v106, 0
	v_mov_b32 v107, 0
	v_mov_b32 v108, 0
	v_mov_b32 v109, 0
	v_mov_b32 v102, 0
	v_mov_b32 v103, 0
	v_mov_b32 v104, 0
	v_mov_b32 v105, 0
	v_mov_b32 v94, 0
	v_mov_b32 v95, 0
	v_mov_b32 v96, 0
	v_mov_b32 v97, 0
	v_mov_b32 v86, 0
	v_mov_b32 v87, 0
	v_mov_b32 v88, 0
	v_mov_b32 v89, 0
	v_mov_b32 v78, 0
	v_mov_b32 v79, 0
	v_mov_b32 v80, 0
	v_mov_b32 v81, 0
	s_branch .LBB0_185

.LBB0_185:
	s_waitcnt vmcnt(0)
	s_barrier
	v_mbcnt_lo_u32_b32 v192, -1, 0
	v_mbcnt_hi_u32_b32 v192, -1, v192
	s_add_i32 s35, 0, 0x10000
	s_add_i32 s37, s35, s61
	s_add_i32 s92, s37, 0x4000
	s_add_u32 s98, s8, s14
	s_addc_u32 s99, s9, s15
	s_add_u32 s100, s8, s28
	s_addc_u32 s101, s9, s29
	s_mov_b32 m0, s37
	s_add_i32 s35, s35, s65
	global_load_lds_dwordx4 v251, s[98:99]
	s_mov_b32 m0, s92
	s_add_i32 s93, s35, 0x4000
	global_load_lds_dwordx4 v251, s[100:101]
	s_mov_b32 m0, s35
	s_add_i32 s36, s68, s79
	global_load_lds_dwordx4 v252, s[98:99]
	s_mov_b32 m0, s93
	s_add_i32 s90, s36, 64
	global_load_lds_dwordx4 v252, s[100:101]
	s_add_i32 s34, s79, 63
	s_mul_hi_i32 s91, s90, 0xa000
	s_mul_i32 s90, s90, 0xa000
	s_add_u32 s90, s82, s90
	s_addc_u32 s91, s83, s91
	s_add_u32 s98, s90, 0x80
	s_addc_u32 s99, s91, 0
	s_add_i32 s94, s47, s70
	s_mov_b32 m0, s94
	s_add_i32 s95, s94, 0x400
	global_load_lds_dwordx4 v253, s[90:91]
	s_mov_b32 m0, s95
	s_add_i32 s96, s47, s74
	global_load_lds_dwordx4 v253, s[98:99]
	s_mov_b32 m0, s96
	s_add_i32 s97, s47, s77
	global_load_lds_dwordx4 v254, s[90:91]
	s_mov_b32 m0, s97
	v_ashrrev_i32_e32 v188, 5, v192
	global_load_lds_dwordx4 v254, s[98:99]
	v_and_b32_e32 v193, 31, v192
	v_lshlrev_b32_e32 v189, 4, v192
	v_lshlrev_b32_e32 v191, 4, v188
	v_lshlrev_b32_e32 v190, 8, v193
	v_bitop3_b32 v2, v189, v191, s48 bitop3:0x6c
	v_add3_u32 v6, s84, v2, v190
	ds_read_b128 v[2:5], v6
	v_xor_b32_e32 v250, 0x80, v6
	ds_read_b128 v[194:197], v250
	s_waitcnt lgkmcnt(0)
	v_mfma_f32_32x32x16_bf16 v[18:33], v[2:5], v[34:37], 0
	ds_read_b128 v[2:5], v6 offset:8192
	ds_read_b128 v[198:201], v250 offset:8192
	v_add_u32_e32 v7, 32, v191
	v_bitop3_b32 v7, v7, v189, s48 bitop3:0x78
	v_add3_u32 v210, s84, v7, v190
	ds_read_b128 v[202:205], v210
	v_xor_b32_e32 v250, 0x80, v210
	ds_read_b128 v[206:209], v250
	v_add_u32_e32 v211, 64, v191
	s_waitcnt lgkmcnt(0)
	v_mfma_f32_32x32x16_bf16 v[18:33], v[202:205], v[38:41], v[18:33]
	ds_read_b128 v[202:205], v210 offset:8192
	v_bitop3_b32 v211, v211, v189, s48 bitop3:0x78
	v_add3_u32 v218, s84, v211, v190
	ds_read_b128 v[210:213], v250 offset:8192
	v_add_u32_e32 v191, 0x60, v191
	v_bitop3_b32 v191, v191, v189, s48 bitop3:0x78
	v_add3_u32 v190, s84, v191, v190
	v_mfma_f32_32x32x16_bf16 v[2:17], v[2:5], v[34:37], 0
	v_add_u32_e32 v189, s81, v189
	s_cmp_le_u32 s34, s59
	s_waitcnt lgkmcnt(0)
	v_mfma_f32_32x32x16_bf16 v[2:17], v[202:205], v[38:41], v[2:17]
	ds_read_b128 v[202:205], v218
	v_xor_b32_e32 v250, 0x80, v218
	ds_read_b128 v[214:217], v250
	s_waitcnt lgkmcnt(0)
	v_mfma_f32_32x32x16_bf16 v[18:33], v[202:205], v[42:45], v[18:33]
	ds_read_b128 v[202:205], v218 offset:8192
	ds_read_b128 v[218:221], v250 offset:8192
	s_waitcnt lgkmcnt(0)
	v_mfma_f32_32x32x16_bf16 v[2:17], v[202:205], v[42:45], v[2:17]
	ds_read_b128 v[202:205], v190
	v_xor_b32_e32 v250, 0x80, v190
	ds_read_b128 v[226:229], v250
	s_waitcnt lgkmcnt(0)
	v_mfma_f32_32x32x16_bf16 v[18:33], v[202:205], v[46:49], v[18:33]
	ds_read_b128 v[202:205], v190 offset:8192
	ds_read_b128 v[230:233], v250 offset:8192
	s_waitcnt lgkmcnt(0)
	v_mfma_f32_32x32x16_bf16 v[2:17], v[202:205], v[46:49], v[2:17]
	v_mfma_f32_32x32x16_bf16 v[18:33], v[194:197], v[50:53], v[18:33]
	v_mfma_f32_32x32x16_bf16 v[2:17], v[198:201], v[50:53], v[2:17]
	ds_read_b128 v[194:197], v189
	ds_read_b128 v[198:201], v189 offset:1024
	v_mfma_f32_32x32x16_bf16 v[18:33], v[206:209], v[54:57], v[18:33]
	v_mfma_f32_32x32x16_bf16 v[2:17], v[210:213], v[54:57], v[2:17]
	s_waitcnt lgkmcnt(0)
	v_mfma_f32_32x32x16_bf16 v[18:33], v[214:217], v[194:197], v[18:33]
	v_mfma_f32_32x32x16_bf16 v[2:17], v[218:221], v[194:197], v[2:17]
	v_mfma_f32_32x32x16_bf16 v[18:33], v[226:229], v[198:201], v[18:33]
	v_mfma_f32_32x32x16_bf16 v[2:17], v[230:233], v[198:201], v[2:17]
	s_cbranch_scc1 .LBB0_187
	v_lshlrev_b32_e32 v188, 2, v188
	v_sub_u32_e32 v188, v193, v188
	v_add_u32_e32 v188, s86, v188
	v_add_u32_e32 v189, 0x80000001, v188
	v_cmp_gt_u32_e32 vcc, s46, v189
	s_nop 4
	v_cndmask_b32_e32 v18, v225, v18, vcc
	v_cmp_lt_i32_e32 vcc, 31, v189
	s_nop 1
	v_cndmask_b32_e32 v2, v225, v2, vcc
	v_cmp_lt_i32_e32 vcc, 0, v189
	v_subrev_u32_e32 v189, 31, v188
	s_nop 0
	v_cndmask_b32_e32 v19, v225, v19, vcc
	v_cmp_lt_u32_e32 vcc, s49, v189
	v_subrev_u32_e32 v189, 32, v188
	s_nop 0
	v_cndmask_b32_e32 v3, v225, v3, vcc
	v_cmp_lt_u32_e32 vcc, s49, v188
	s_nop 1
	v_cndmask_b32_e32 v20, v225, v20, vcc
	v_cmp_lt_u32_e32 vcc, s49, v189
	v_add_u32_e32 v189, -1, v188
	s_nop 0
	v_cndmask_b32_e32 v4, v225, v4, vcc
	v_cmp_lt_u32_e32 vcc, s49, v189
	v_subrev_u32_e32 v189, 33, v188
	s_nop 0
	v_cndmask_b32_e32 v21, v225, v21, vcc
	v_cmp_lt_u32_e32 vcc, s49, v189
	v_add_u32_e32 v189, -6, v188
	s_nop 0
	v_cndmask_b32_e32 v5, v225, v5, vcc
	v_cmp_lt_u32_e32 vcc, s49, v189
	v_subrev_u32_e32 v189, 38, v188
	s_nop 0
	v_cndmask_b32_e32 v22, v225, v22, vcc
	v_cmp_lt_u32_e32 vcc, s49, v189
	v_add_u32_e32 v189, -7, v188
	s_nop 0
	v_cndmask_b32_e32 v6, v225, v6, vcc
	v_cmp_lt_u32_e32 vcc, s49, v189
	v_subrev_u32_e32 v189, 39, v188
	s_nop 0
	v_cndmask_b32_e32 v23, v225, v23, vcc
	v_cmp_lt_u32_e32 vcc, s49, v189
	v_add_u32_e32 v189, -8, v188
	s_nop 0
	v_cndmask_b32_e32 v7, v225, v7, vcc
	v_cmp_lt_u32_e32 vcc, s49, v189
	v_subrev_u32_e32 v189, 40, v188
	s_nop 0
	v_cndmask_b32_e32 v24, v225, v24, vcc
	v_cmp_lt_u32_e32 vcc, s49, v189
	v_add_u32_e32 v189, -9, v188
	s_nop 0
	v_cndmask_b32_e32 v8, v225, v8, vcc
	v_cmp_lt_u32_e32 vcc, s49, v189
	v_subrev_u32_e32 v189, 41, v188
	s_nop 0
	v_cndmask_b32_e32 v25, v225, v25, vcc
	v_cmp_lt_u32_e32 vcc, s49, v189
	v_add_u32_e32 v189, -14, v188
	s_nop 0
	v_cndmask_b32_e32 v9, v225, v9, vcc
	v_cmp_lt_u32_e32 vcc, s49, v189
	v_subrev_u32_e32 v189, 46, v188
	s_nop 0
	v_cndmask_b32_e32 v26, v225, v26, vcc
	v_cmp_lt_u32_e32 vcc, s49, v189
	v_add_u32_e32 v189, -15, v188
	s_nop 0
	v_cndmask_b32_e32 v10, v225, v10, vcc
	v_cmp_lt_u32_e32 vcc, s49, v189
	v_subrev_u32_e32 v189, 47, v188
	s_nop 0
	v_cndmask_b32_e32 v27, v225, v27, vcc
	v_cmp_lt_u32_e32 vcc, s49, v189
	v_add_u32_e32 v189, -16, v188
	s_nop 0
	v_cndmask_b32_e32 v11, v225, v11, vcc
	v_cmp_lt_u32_e32 vcc, s49, v189
	v_subrev_u32_e32 v189, 48, v188
	s_nop 0
	v_cndmask_b32_e32 v28, v225, v28, vcc
	v_cmp_lt_u32_e32 vcc, s49, v189
	v_subrev_u32_e32 v189, 17, v188
	s_nop 0
	v_cndmask_b32_e32 v12, v225, v12, vcc
	v_cmp_lt_u32_e32 vcc, s49, v189
	v_subrev_u32_e32 v189, 49, v188
	s_nop 0
	v_cndmask_b32_e32 v29, v225, v29, vcc
	v_cmp_lt_u32_e32 vcc, s49, v189
	v_subrev_u32_e32 v189, 22, v188
	s_nop 0
	v_cndmask_b32_e32 v13, v225, v13, vcc
	v_cmp_lt_u32_e32 vcc, s49, v189
	v_subrev_u32_e32 v189, 54, v188
	s_nop 0
	v_cndmask_b32_e32 v30, v225, v30, vcc
	v_cmp_lt_u32_e32 vcc, s49, v189
	v_subrev_u32_e32 v189, 23, v188
	s_nop 0
	v_cndmask_b32_e32 v14, v225, v14, vcc
	v_cmp_lt_u32_e32 vcc, s49, v189
	v_subrev_u32_e32 v189, 55, v188
	s_nop 0
	v_cndmask_b32_e32 v31, v225, v31, vcc
	v_cmp_lt_u32_e32 vcc, s49, v189
	v_subrev_u32_e32 v189, 24, v188
	s_nop 0
	v_cndmask_b32_e32 v15, v225, v15, vcc
	v_cmp_lt_u32_e32 vcc, s49, v189
	v_subrev_u32_e32 v189, 56, v188
	s_nop 0
	v_cndmask_b32_e32 v32, v225, v32, vcc
	v_cmp_lt_u32_e32 vcc, s49, v189
	v_subrev_u32_e32 v189, 25, v188
	v_subrev_u32_e32 v188, 57, v188
	v_cndmask_b32_e32 v16, v225, v16, vcc
	v_cmp_lt_u32_e32 vcc, s49, v189
	s_nop 1
	v_cndmask_b32_e32 v33, v225, v33, vcc
	v_cmp_lt_u32_e32 vcc, s49, v188
	s_nop 1
	v_cndmask_b32_e32 v17, v225, v17, vcc

.LBB0_194:
	v_ashrrev_i32_e32 v193, 5, v192
	v_and_b32_e32 v194, 31, v192
	v_lshlrev_b32_e32 v195, 4, v192
	v_lshlrev_b32_e32 v221, 4, v193
	v_lshlrev_b32_e32 v220, 8, v194
	v_bitop3_b32 v2, v195, v221, s48 bitop3:0x6c
	v_add3_u32 v6, s85, v2, v220
	ds_read_b128 v[2:5], v6
	v_xor_b32_e32 v250, 0x80, v6
	ds_read_b128 v[196:199], v250
	s_waitcnt lgkmcnt(0)
	v_mfma_f32_32x32x16_bf16 v[18:33], v[2:5], v[34:37], 0
	ds_read_b128 v[2:5], v6 offset:8192
	ds_read_b128 v[200:203], v250 offset:8192
	v_add_u32_e32 v7, 32, v221
	v_bitop3_b32 v7, v7, v195, s48 bitop3:0x78
	v_add3_u32 v212, s85, v7, v220
	ds_read_b128 v[204:207], v212
	v_xor_b32_e32 v250, 0x80, v212
	ds_read_b128 v[208:211], v250
	v_add_u32_e32 v213, 64, v221
	s_waitcnt lgkmcnt(0)
	v_mfma_f32_32x32x16_bf16 v[18:33], v[204:207], v[38:41], v[18:33]
	ds_read_b128 v[204:207], v212 offset:8192
	v_bitop3_b32 v213, v213, v195, s48 bitop3:0x78
	v_add3_u32 v222, s85, v213, v220
	ds_read_b128 v[212:215], v250 offset:8192
	v_add_u32_e32 v221, 0x60, v221
	v_bitop3_b32 v221, v221, v195, s48 bitop3:0x78
	v_add3_u32 v220, s85, v221, v220
	v_mfma_f32_32x32x16_bf16 v[2:17], v[2:5], v[34:37], 0
	v_add_u32_e32 v195, s81, v195
	s_add_i32 s36, s79, 0x7f
	s_cmp_le_u32 s36, s59
	s_waitcnt lgkmcnt(0)
	v_mfma_f32_32x32x16_bf16 v[2:17], v[204:207], v[38:41], v[2:17]
	ds_read_b128 v[204:207], v222
	v_xor_b32_e32 v250, 0x80, v222
	ds_read_b128 v[216:219], v250
	ds_read_b128 v[226:229], v250 offset:8192
	s_waitcnt lgkmcnt(0)
	v_mfma_f32_32x32x16_bf16 v[18:33], v[204:207], v[42:45], v[18:33]
	ds_read_b128 v[204:207], v222 offset:8192
	s_waitcnt lgkmcnt(0)
	v_mfma_f32_32x32x16_bf16 v[2:17], v[204:207], v[42:45], v[2:17]
	ds_read_b128 v[204:207], v220
	v_xor_b32_e32 v250, 0x80, v220
	ds_read_b128 v[230:233], v250
	s_waitcnt lgkmcnt(0)
	v_mfma_f32_32x32x16_bf16 v[18:33], v[204:207], v[46:49], v[18:33]
	ds_read_b128 v[204:207], v220 offset:8192
	ds_read_b128 v[234:237], v250 offset:8192
	s_waitcnt lgkmcnt(0)
	v_mfma_f32_32x32x16_bf16 v[2:17], v[204:207], v[46:49], v[2:17]
	v_mfma_f32_32x32x16_bf16 v[18:33], v[196:199], v[50:53], v[18:33]
	v_mfma_f32_32x32x16_bf16 v[2:17], v[200:203], v[50:53], v[2:17]
	ds_read_b128 v[196:199], v195
	ds_read_b128 v[200:203], v195 offset:1024
	v_mfma_f32_32x32x16_bf16 v[18:33], v[208:211], v[54:57], v[18:33]
	v_mfma_f32_32x32x16_bf16 v[2:17], v[212:215], v[54:57], v[2:17]
	s_waitcnt lgkmcnt(0)
	v_mfma_f32_32x32x16_bf16 v[18:33], v[216:219], v[196:199], v[18:33]
	v_mfma_f32_32x32x16_bf16 v[2:17], v[226:229], v[196:199], v[2:17]
	v_mfma_f32_32x32x16_bf16 v[18:33], v[230:233], v[200:203], v[18:33]
	v_mfma_f32_32x32x16_bf16 v[2:17], v[234:237], v[200:203], v[2:17]
	s_cbranch_scc1 .LBB0_196
	v_lshlrev_b32_e32 v193, 2, v193
	v_sub_u32_e32 v193, v194, v193
	v_add_u32_e32 v193, s86, v193
	v_add_u32_e32 v195, 0x7fffffc1, v193
	v_cmp_gt_u32_e32 vcc, s46, v195
	s_nop 4
	v_cndmask_b32_e32 v18, v225, v18, vcc
	v_cmp_lt_i32_e32 vcc, 31, v195
	s_nop 1
	v_cndmask_b32_e32 v2, v225, v2, vcc
	v_cmp_lt_i32_e32 vcc, 0, v195
	v_add_u32_e32 v195, 0xffffffa1, v193
	s_nop 0
	v_cndmask_b32_e32 v19, v225, v19, vcc
	v_cmp_lt_u32_e32 vcc, s49, v195
	v_subrev_u32_e32 v195, 64, v193
	s_nop 0
	v_cndmask_b32_e32 v3, v225, v3, vcc
	v_cmp_lt_u32_e32 vcc, s49, v195
	v_add_u32_e32 v195, 0xffffffa0, v193
	s_nop 0
	v_cndmask_b32_e32 v20, v225, v20, vcc
	v_cmp_lt_u32_e32 vcc, s49, v195
	v_add_u32_e32 v195, 0xffffffbf, v193
	s_nop 0
	v_cndmask_b32_e32 v4, v225, v4, vcc
	v_cmp_lt_u32_e32 vcc, s49, v195
	v_add_u32_e32 v195, 0xffffff9f, v193
	s_nop 0
	v_cndmask_b32_e32 v21, v225, v21, vcc
	v_cmp_lt_u32_e32 vcc, s49, v195
	v_add_u32_e32 v195, 0xffffffba, v193
	s_nop 0
	v_cndmask_b32_e32 v5, v225, v5, vcc
	v_cmp_lt_u32_e32 vcc, s49, v195
	v_add_u32_e32 v195, 0xffffff9a, v193
	s_nop 0
	v_cndmask_b32_e32 v22, v225, v22, vcc
	v_cmp_lt_u32_e32 vcc, s49, v195
	v_add_u32_e32 v195, 0xffffffb9, v193
	s_nop 0
	v_cndmask_b32_e32 v6, v225, v6, vcc
	v_cmp_lt_u32_e32 vcc, s49, v195
	v_add_u32_e32 v195, 0xffffff99, v193
	s_nop 0
	v_cndmask_b32_e32 v23, v225, v23, vcc
	v_cmp_lt_u32_e32 vcc, s49, v195
	v_add_u32_e32 v195, 0xffffffb8, v193
	s_nop 0
	v_cndmask_b32_e32 v7, v225, v7, vcc
	v_cmp_lt_u32_e32 vcc, s49, v195
	v_add_u32_e32 v195, 0xffffff98, v193
	s_nop 0
	v_cndmask_b32_e32 v24, v225, v24, vcc
	v_cmp_lt_u32_e32 vcc, s49, v195
	v_add_u32_e32 v195, 0xffffffb7, v193
	s_nop 0
	v_cndmask_b32_e32 v8, v225, v8, vcc
	v_cmp_lt_u32_e32 vcc, s49, v195
	v_add_u32_e32 v195, 0xffffff97, v193
	s_nop 0
	v_cndmask_b32_e32 v25, v225, v25, vcc
	v_cmp_lt_u32_e32 vcc, s49, v195
	v_add_u32_e32 v195, 0xffffffb2, v193
	s_nop 0
	v_cndmask_b32_e32 v9, v225, v9, vcc
	v_cmp_lt_u32_e32 vcc, s49, v195
	v_add_u32_e32 v195, 0xffffff92, v193
	s_nop 0
	v_cndmask_b32_e32 v26, v225, v26, vcc
	v_cmp_lt_u32_e32 vcc, s49, v195
	v_add_u32_e32 v195, 0xffffffb1, v193
	s_nop 0
	v_cndmask_b32_e32 v10, v225, v10, vcc
	v_cmp_lt_u32_e32 vcc, s49, v195
	v_add_u32_e32 v195, 0xffffff91, v193
	s_nop 0
	v_cndmask_b32_e32 v27, v225, v27, vcc
	v_cmp_lt_u32_e32 vcc, s49, v195
	v_add_u32_e32 v195, 0xffffffb0, v193
	s_nop 0
	v_cndmask_b32_e32 v11, v225, v11, vcc
	v_cmp_lt_u32_e32 vcc, s49, v195
	v_add_u32_e32 v195, 0xffffff90, v193
	s_nop 0
	v_cndmask_b32_e32 v28, v225, v28, vcc
	v_cmp_lt_u32_e32 vcc, s49, v195
	v_add_u32_e32 v195, 0xffffffaf, v193
	s_nop 0
	v_cndmask_b32_e32 v12, v225, v12, vcc
	v_cmp_lt_u32_e32 vcc, s49, v195
	v_add_u32_e32 v195, 0xffffff8f, v193
	s_nop 0
	v_cndmask_b32_e32 v29, v225, v29, vcc
	v_cmp_lt_u32_e32 vcc, s49, v195
	v_add_u32_e32 v195, 0xffffffaa, v193
	s_nop 0
	v_cndmask_b32_e32 v13, v225, v13, vcc
	v_cmp_lt_u32_e32 vcc, s49, v195
	v_add_u32_e32 v195, 0xffffff8a, v193
	s_nop 0
	v_cndmask_b32_e32 v30, v225, v30, vcc
	v_cmp_lt_u32_e32 vcc, s49, v195
	v_add_u32_e32 v195, 0xffffffa9, v193
	s_nop 0
	v_cndmask_b32_e32 v14, v225, v14, vcc
	v_cmp_lt_u32_e32 vcc, s49, v195
	v_add_u32_e32 v195, 0xffffff89, v193
	s_nop 0
	v_cndmask_b32_e32 v31, v225, v31, vcc
	v_cmp_lt_u32_e32 vcc, s49, v195
	v_add_u32_e32 v195, 0xffffffa8, v193
	s_nop 0
	v_cndmask_b32_e32 v15, v225, v15, vcc
	v_cmp_lt_u32_e32 vcc, s49, v195
	v_add_u32_e32 v195, 0xffffff88, v193
	s_nop 0
	v_cndmask_b32_e32 v32, v225, v32, vcc
	v_cmp_lt_u32_e32 vcc, s49, v195
	v_add_u32_e32 v195, 0xffffffa7, v193
	v_add_u32_e32 v193, 0xffffff87, v193
	v_cndmask_b32_e32 v16, v225, v16, vcc
	v_cmp_lt_u32_e32 vcc, s49, v195
	s_nop 1
	v_cndmask_b32_e32 v33, v225, v33, vcc
	v_cmp_lt_u32_e32 vcc, s49, v193
	s_nop 1
	v_cndmask_b32_e32 v17, v225, v17, vcc
